# baseline (speedup 1.0000x reference)
; DEV int v_st(int k, int c) { const int kk = (k & ~0xC) | ((k & 4) << 1) | ((k & 8) >> 1); return ((kk >> 3) * 4 + (c >> 5)) * 512 + ((kk & 7) * 32 + (c & 31)) * 2; }
; DEV int v_rd_base(int lane) { return ((lane & 3) << 3) | (((lane >> 2) & 3) << 6) | (((lane >> 4) & 1) << 5) | (((lane >> 5) & 1) << 8); }
; #define SWRITE(b) do { *reinterpret_cast<bf16x8*>(V_lds + (b) * 16384 + vst0) = sv0; *reinterpret_cast<bf16x8*>(V_lds + (b) * 16384 + vst1) = sv1; \
;     *reinterpret_cast<bf16x8*>(K_lds + (b) * 16384 + kst0) = sk0; if (SB) *reinterpret_cast<bf16x8*>(K_lds + (b) * 16384 + kst1) = sk1; } while (0)
; template <bool SB>
; DEV void attn_pass(const bf16_t* __restrict__ proj, int qcol, int kcol, int vcol, int q0, f32x16 (&o)[4], float& l_out, unsigned char* lds) {
;     ...
;   { const bf16_t* Qw = proj + (size_t)(q0 + wid * 32 + r32) * INW + qcol + hi * 8;
; #pragma unroll
;     for (int d0 = 0; d0 < NDK; ++d0) qr[d0] = *reinterpret_cast<const bf16x8*>(Qw + d0 * 16); }
;   const int c0 = q0 >> 6, jhi = c0 + 3, jw = c0 + (wid >> 1);
;   const int sr = tid >> 4, sc = (tid & 15) * 8, vst0 = v_st(sr, sc), vst1 = v_st(32 + sr, sc);
;   const int kr = SB ? sr : (tid >> 3), kc = SB ? sc : (tid & 7) * 8;
;   const int kst0 = kr * KROWB + ((kc * 2) ^ ((kr & 7) << 4)), kst1 = (32 + kr) * KROWB + ((kc * 2) ^ ((kr & 7) << 4));
;   const int vb0 = (int)(uintptr_t)V_lds + v_rd_base(lane);
;   bf16x8 sv0, sv1, sk0, sk1;
;     ...
;   float m_reg = -1e30f, l_reg = 0.f, cum = 1.f;
; #pragma unroll
;   for (int d = 0; d < 4; ++d) o[d] = f32x16{};
;   SLOAD(jhi); SWRITE(0); __syncthreads();
.LBB0_351:
	s_and_b64 s[4:5], s[0:1], exec
	v_readlane_b32 s4, v255, 43
	v_readlane_b32 s5, v255, 44
	s_cselect_b32 s81, s5, s4
	s_lshl_b32 s75, s81, 2
	v_mov_b32_e32 v66, v210
	s_or_b32 s78, s75, 3
	s_ashr_i32 s79, s78, 31
	v_ashrrev_i32_e32 v144, 4, v66
	v_lshlrev_b32_e32 v8, 3, v66
	v_and_b32_e32 v0, 0x78, v8
	s_lshl_b64 s[4:5], s[78:79], 6
	v_ashrrev_i32_e32 v145, 31, v144
	v_lshlrev_b32_e32 v192, 1, v0
	v_lshl_add_u64 v[0:1], s[4:5], 0, v[144:145]
	v_mov_b64_e32 v[2:3], s[86:87]
	v_mad_u64_u32 v[4:5], s[6:7], v0, s85, v[2:3]
	v_lshl_add_u64 v[146:147], v[144:145], 0, 32
	v_readlane_b32 s6, v255, 46
	v_lshl_add_u64 v[6:7], v[146:147], 0, s[4:5]
	v_mad_i32_i24 v5, v1, s85, v5
	s_lshl_b32 s76, s6, 1
	v_mad_u64_u32 v[2:3], s[4:5], v6, s85, v[2:3]
	v_lshl_add_u64 v[0:1], v[4:5], 0, s[76:77]
	v_mad_i32_i24 v3, v7, s85, v3
	v_readlane_b32 s4, v255, 53
	v_lshl_add_u64 v[0:1], v[0:1], 0, v[192:193]
	v_lshl_add_u64 v[6:7], v[2:3], 0, s[76:77]
	s_lshl_b32 s82, s4, 1
	s_mov_b32 s83, s77
	v_lshl_add_u64 v[6:7], v[6:7], 0, v[192:193]
	global_load_dwordx4 v[96:99], v[0:1], off
	global_load_dwordx4 v[100:103], v[6:7], off
	v_lshl_add_u64 v[0:1], v[4:5], 0, s[82:83]
	v_lshl_add_u64 v[2:3], v[2:3], 0, s[82:83]
	v_lshl_add_u64 v[0:1], v[0:1], 0, v[192:193]
	v_lshl_add_u64 v[2:3], v[2:3], 0, v[192:193]
	v_readlane_b32 s4, v255, 55
	s_lshl_b32 s74, s81, 8
	v_ashrrev_i32_e32 v70, 6, v66
	v_and_b32_e32 v68, 31, v66
	global_load_dwordx4 v[104:107], v[0:1], off offset:2048
	global_load_dwordx4 v[108:111], v[2:3], off offset:2048
	v_readlane_b32 s5, v255, 56
	v_lshlrev_b32_e32 v69, 5, v70
	v_or_b32_e32 v3, s74, v68
	v_mov_b64_e32 v[0:1], s[4:5]
	v_bfe_u32 v67, v66, 5, 1
	v_add_u32_e32 v3, v3, v69
	v_mov_b32_e32 v65, v193
	v_lshlrev_b32_e32 v64, 4, v67
	v_mad_i64_i32 v[0:1], s[4:5], v3, s85, v[0:1]
	v_lshl_add_u64 v[0:1], v[0:1], 0, v[64:65]
	global_load_dwordx4 v[112:115], v[0:1], off
	global_load_dwordx4 v[116:119], v[0:1], off offset:32
	global_load_dwordx4 v[120:123], v[0:1], off offset:64
	global_load_dwordx4 v[124:127], v[0:1], off offset:96
	global_load_dwordx4 v[128:131], v[0:1], off offset:128
	global_load_dwordx4 v[132:135], v[0:1], off offset:160
	global_load_dwordx4 v[136:139], v[0:1], off offset:192
	global_load_dwordx4 v[140:143], v[0:1], off offset:224
	v_and_b32_e32 v4, 0xfffff0, v144
	v_lshlrev_b32_e32 v5, 1, v144
	v_lshrrev_b32_e32 v6, 1, v144
	v_bfe_u32 v7, v8, 5, 2
	v_and_b32_e32 v8, 3, v144
	v_add_u32_e32 v9, 32, v144
	v_and_or_b32 v4, v5, 8, v4
	v_and_or_b32 v5, v6, 4, v8
	v_and_b32_e32 v6, 0xfffff0, v9
	v_lshlrev_b32_e32 v8, 1, v9
	v_and_b32_e32 v2, 0x70, v66
	v_lshlrev_b32_e32 v10, 8, v144
	v_lshlrev_b32_e32 v9, 8, v9
	v_lshrrev_b32_e32 v3, 1, v4
	v_and_or_b32 v6, v8, 8, v6
	v_bitop3_b32 v188, v192, v9, v2 bitop3:0xde
	v_bitop3_b32 v189, v192, v10, v2 bitop3:0xde
	v_or_b32_e32 v2, v3, v7
	v_lshrrev_b32_e32 v3, 1, v6
	v_or_b32_e32 v1, v3, v7
	v_lshlrev_b32_e32 v4, 6, v5
	v_and_b32_e32 v5, 48, v192
	v_lshlrev_b32_e32 v0, 9, v2
	v_lshlrev_b32_e32 v1, 9, v1
	v_or3_b32 v190, v0, v4, v5
	v_or3_b32 v191, v1, v4, v5
	v_add_u32_e32 v6, 0, v189
	v_add_u32_e32 v8, 0, v188
	v_add_u32_e32 v0, 0, v190
	v_add_u32_e32 v1, 0, v191
	v_mov_b32_e32 v31, 0
	s_cmp_lt_i32 s81, 0
	v_mov_b32_e32 v30, v31
	v_mov_b32_e32 v29, v31
	v_mov_b32_e32 v28, v31
	v_mov_b32_e32 v27, v31
	v_mov_b32_e32 v26, v31
	v_mov_b32_e32 v25, v31
	v_mov_b32_e32 v24, v31
	s_waitcnt vmcnt(11)
	ds_write_b128 v0, v[96:99]
	s_waitcnt vmcnt(10)
	ds_write_b128 v1, v[100:103]
	s_waitcnt vmcnt(9)
	ds_write_b128 v6, v[104:107] offset:32768
	s_waitcnt vmcnt(8)
	ds_write_b128 v8, v[108:111] offset:32768
	v_mov_b32_e32 v23, v31
	v_mov_b32_e32 v22, v31
	v_mov_b32_e32 v21, v31
	v_mov_b32_e32 v20, v31
	v_mov_b32_e32 v19, v31
	v_mov_b32_e32 v18, v31
	v_mov_b32_e32 v17, v31
	v_mov_b32_e32 v16, v31
	v_mov_b32_e32 v63, v31
	v_mov_b32_e32 v62, v31
	v_mov_b32_e32 v61, v31
	v_mov_b32_e32 v60, v31
	v_mov_b32_e32 v59, v31
	v_mov_b32_e32 v58, v31
	v_mov_b32_e32 v57, v31
	v_mov_b32_e32 v56, v31
	v_mov_b32_e32 v55, v31
	v_mov_b32_e32 v54, v31
	v_mov_b32_e32 v53, v31
	v_mov_b32_e32 v52, v31
	v_mov_b32_e32 v51, v31
	v_mov_b32_e32 v50, v31
	v_mov_b32_e32 v49, v31
	v_mov_b32_e32 v48, v31
	v_mov_b32_e32 v47, v31
	v_mov_b32_e32 v46, v31
	v_mov_b32_e32 v45, v31
	v_mov_b32_e32 v44, v31
	v_mov_b32_e32 v43, v31
	v_mov_b32_e32 v42, v31
	v_mov_b32_e32 v41, v31
	v_mov_b32_e32 v40, v31
	v_mov_b32_e32 v39, v31
	v_mov_b32_e32 v38, v31
	v_mov_b32_e32 v37, v31
	v_mov_b32_e32 v36, v31
	v_mov_b32_e32 v35, v31
	v_mov_b32_e32 v34, v31
	v_mov_b32_e32 v33, v31
	v_mov_b32_e32 v32, v31
	v_mov_b32_e32 v15, v31
	v_mov_b32_e32 v14, v31
	v_mov_b32_e32 v13, v31
	v_mov_b32_e32 v12, v31
	v_mov_b32_e32 v11, v31
	v_mov_b32_e32 v10, v31
	v_mov_b32_e32 v9, v31
	v_mov_b32_e32 v8, v31
	v_mov_b32_e32 v7, v31
	v_mov_b32_e32 v6, v31
	v_mov_b32_e32 v5, v31
	v_mov_b32_e32 v4, v31
	v_mov_b32_e32 v3, v31
	v_mov_b32_e32 v2, v31
	v_mov_b32_e32 v1, v31
	v_mov_b32_e32 v0, v31
	s_waitcnt lgkmcnt(0)
	s_barrier
; DEV int v_st(int k, int c) { const int kk = (k & ~0xC) | ((k & 4) << 1) | ((k & 8) >> 1); return ((kk >> 3) * 4 + (c >> 5)) * 512 + ((kk & 7) * 32 + (c & 31)) * 2; }
; DEV int v_rd_base(int lane) { return ((lane & 3) << 3) | (((lane >> 2) & 3) << 6) | (((lane >> 4) & 1) << 5) | (((lane >> 5) & 1) << 8); }
; #define SWRITE(b) do { *reinterpret_cast<bf16x8*>(V_lds + (b) * 16384 + vst0) = sv0; *reinterpret_cast<bf16x8*>(V_lds + (b) * 16384 + vst1) = sv1; \
;     *reinterpret_cast<bf16x8*>(K_lds + (b) * 16384 + kst0) = sk0; if (SB) *reinterpret_cast<bf16x8*>(K_lds + (b) * 16384 + kst1) = sk1; } while (0)
; template <bool SB>
; DEV void attn_pass(const bf16_t* __restrict__ proj, int qcol, int kcol, int vcol, int q0, f32x16 (&o)[4], float& l_out, unsigned char* lds) {
;     ...
;   const int c0 = q0 >> 6, jhi = c0 + 3, jw = c0 + (wid >> 1);
;   const int sr = tid >> 4, sc = (tid & 15) * 8, vst0 = v_st(sr, sc), vst1 = v_st(32 + sr, sc);
;   const int kr = SB ? sr : (tid >> 3), kc = SB ? sc : (tid & 7) * 8;
;   const int kst0 = kr * KROWB + ((kc * 2) ^ ((kr & 7) << 4)), kst1 = (32 + kr) * KROWB + ((kc * 2) ^ ((kr & 7) << 4));
;   const int vb0 = (int)(uintptr_t)V_lds + v_rd_base(lane);
;   bf16x8 sv0, sv1, sk0, sk1;
;     ...
;   float m_reg = -1e30f, l_reg = 0.f, cum = 1.f;
; #pragma unroll
;   for (int d = 0; d < 4; ++d) o[d] = f32x16{};
;   SLOAD(jhi); SWRITE(0); __syncthreads();
;   for (int it = 0; it <= jhi; ++it) {
	s_cbranch_scc1 .LBB0_366
	v_and_b32_e32 v0, 63, v66
	v_readlane_b32 s4, v255, 9
	v_lshlrev_b32_e32 v8, 2, v67
	v_lshlrev_b32_e32 v2, 1, v0
	v_lshl_add_u32 v209, v70, 2, s4
	v_lshlrev_b32_e32 v3, 4, v0
	v_lshlrev_b32_e32 v4, 3, v0
	v_and_or_b32 v7, v69, 32, v68
	v_cmp_gt_u32_e64 s[4:5], 32, v0
	v_cmp_eq_u32_e64 s[6:7], 0, v0
	v_or_b32_e32 v0, 1, v8
	v_cmp_lt_u32_e64 s[10:11], v0, v7
	v_or_b32_e32 v0, 2, v8
	v_cmp_lt_u32_e64 s[12:13], v0, v7
	v_or_b32_e32 v0, 3, v8
	v_cmp_lt_u32_e64 s[14:15], v0, v7
	v_or_b32_e32 v0, 9, v8
	v_cmp_lt_u32_e64 s[18:19], v0, v7
	v_or_b32_e32 v0, 10, v8
	v_cmp_lt_u32_e64 s[20:21], v0, v7
	v_or_b32_e32 v0, 11, v8
	v_cmp_lt_u32_e64 s[22:23], v0, v7
	v_or_b32_e32 v0, 17, v8
	v_cmp_lt_u32_e64 s[26:27], v0, v7
	v_or_b32_e32 v0, 18, v8
	v_cmp_lt_u32_e64 s[28:29], v0, v7
	v_or_b32_e32 v0, 19, v8
	v_cmp_lt_u32_e64 s[30:31], v0, v7
	v_or_b32_e32 v0, 25, v8
	v_cmp_lt_u32_e64 s[36:37], v0, v7
	v_or_b32_e32 v0, 26, v8
	v_cmp_lt_u32_e64 s[38:39], v0, v7
	v_or_b32_e32 v0, 27, v8
	v_cmp_lt_u32_e64 s[40:41], v0, v7
	v_or_b32_e32 v0, 33, v8
	v_cmp_lt_u32_e64 s[44:45], v0, v7
	v_or_b32_e32 v0, 34, v8
	v_cmp_lt_u32_e64 s[46:47], v0, v7
	v_or_b32_e32 v0, 35, v8
	v_cmp_lt_u32_e64 s[48:49], v0, v7
	v_or_b32_e32 v0, 41, v8
	v_cmp_lt_u32_e64 s[52:53], v0, v7
	v_or_b32_e32 v0, 42, v8
	v_cmp_lt_u32_e64 s[54:55], v0, v7
	v_or_b32_e32 v0, 43, v8
	v_cmp_lt_u32_e64 s[56:57], v0, v7
	v_or_b32_e32 v0, 49, v8
	v_cmp_lt_u32_e64 s[60:61], v0, v7
	v_or_b32_e32 v0, 50, v8
	v_lshlrev_b32_e32 v5, 4, v66
	s_movk_i32 s8, 0x70
	v_cmp_lt_u32_e64 s[62:63], v0, v7
	v_or_b32_e32 v0, 51, v8
	v_and_b32_e32 v6, 0x70, v5
	v_bitop3_b32 v224, v64, v5, s8 bitop3:0x78
	s_movk_i32 s8, 0x60
	v_cmp_lt_u32_e64 s[64:65], v0, v7
	v_or_b32_e32 v0, 57, v8
	v_bitop3_b32 v227, v64, v6, s8 bitop3:0x36
	s_movk_i32 s8, 0x80
	v_cmp_lt_u32_e64 s[68:69], v0, v7
	v_or_b32_e32 v0, 58, v8
	v_and_b32_e32 v2, 32, v2
	v_bitop3_b32 v228, v64, v6, s8 bitop3:0x36
	s_movk_i32 s8, 0xa0
	v_cmp_lt_u32_e64 s[70:71], v0, v7
	v_or_b32_e32 v0, 59, v8
	s_movk_i32 s83, 0x118
	s_cmp_lg_u32 0, -1
	v_and_b32_e32 v3, 0xc0, v3
	v_bitop3_b32 v229, v64, v6, s8 bitop3:0x36
	s_movk_i32 s8, 0xc0
	v_cmp_lt_u32_e64 s[72:73], v0, v7
	v_and_or_b32 v0, v4, s83, v2
	s_cselect_b32 s83, 0, 0
	v_ashrrev_i32_e32 v1, 7, v66
	v_or_b32_e32 v9, 8, v8
	v_or_b32_e32 v10, 16, v8
	v_or_b32_e32 v11, 24, v8
	v_or_b32_e32 v12, 32, v8
	v_or_b32_e32 v13, 40, v8
	v_or_b32_e32 v14, 48, v8
	v_or_b32_e32 v15, 56, v8
	v_bitop3_b32 v230, v64, v6, s8 bitop3:0x36
	s_movk_i32 s8, 0xe0
	v_add3_u32 v232, v3, s83, v0
	v_mov_b32_e32 v0, 0
	v_add_u32_e32 v208, s75, v1
	v_lshl_add_u32 v223, v68, 8, 0
	s_mov_b32 s79, 0
	v_bitop3_b32 v225, v64, v6, 32 bitop3:0x36
	v_bitop3_b32 v226, v64, v6, 64 bitop3:0x36
	v_bitop3_b32 v231, v64, v6, s8 bitop3:0x36
	v_cmp_lt_u32_e64 s[8:9], v8, v7
	v_cmp_lt_u32_e64 s[16:17], v9, v7
	v_cmp_lt_u32_e64 s[24:25], v10, v7
	v_cmp_lt_u32_e64 s[34:35], v11, v7
	v_cmp_lt_u32_e64 s[42:43], v12, v7
	v_cmp_lt_u32_e64 s[50:51], v13, v7
	v_cmp_lt_u32_e64 s[58:59], v14, v7
	v_cmp_lt_u32_e64 s[66:67], v15, v7
	v_sub_u32_e32 v233, 3, v1
	v_mov_b32_e32 v234, 1.0
	s_mov_b32 s84, s78
	v_mov_b32_e32 v1, v0
	v_mov_b32_e32 v2, v0
	v_mov_b32_e32 v3, v0
	v_mov_b32_e32 v4, v0
	v_mov_b32_e32 v5, v0
	v_mov_b32_e32 v6, v0
	v_mov_b32_e32 v7, v0
	v_mov_b32_e32 v8, v0
	v_mov_b32_e32 v9, v0
	v_mov_b32_e32 v10, v0
	v_mov_b32_e32 v11, v0
	v_mov_b32_e32 v12, v0
	v_mov_b32_e32 v13, v0
	v_mov_b32_e32 v14, v0
	v_mov_b32_e32 v15, v0
	v_mov_b32_e32 v32, v0
	v_mov_b32_e32 v33, v0
	v_mov_b32_e32 v34, v0
	v_mov_b32_e32 v35, v0
	v_mov_b32_e32 v36, v0
	v_mov_b32_e32 v37, v0
	v_mov_b32_e32 v38, v0
	v_mov_b32_e32 v39, v0
	v_mov_b32_e32 v40, v0
	v_mov_b32_e32 v41, v0
	v_mov_b32_e32 v42, v0
	v_mov_b32_e32 v43, v0
	v_mov_b32_e32 v44, v0
	v_mov_b32_e32 v45, v0
	v_mov_b32_e32 v46, v0
	v_mov_b32_e32 v47, v0
	v_mov_b32_e32 v48, v0
	v_mov_b32_e32 v49, v0
	v_mov_b32_e32 v50, v0
	v_mov_b32_e32 v51, v0
	v_mov_b32_e32 v52, v0
	v_mov_b32_e32 v53, v0
	v_mov_b32_e32 v54, v0
	v_mov_b32_e32 v55, v0
	v_mov_b32_e32 v56, v0
	v_mov_b32_e32 v57, v0
	v_mov_b32_e32 v58, v0
	v_mov_b32_e32 v59, v0
	v_mov_b32_e32 v60, v0
	v_mov_b32_e32 v61, v0
	v_mov_b32_e32 v62, v0
	v_mov_b32_e32 v63, v0
	v_mov_b32_e32 v16, v0
	v_mov_b32_e32 v17, v0
	v_mov_b32_e32 v18, v0
	v_mov_b32_e32 v19, v0
	v_mov_b32_e32 v20, v0
	v_mov_b32_e32 v21, v0
	v_mov_b32_e32 v22, v0
	v_mov_b32_e32 v23, v0
	v_mov_b32_e32 v24, v0
	v_mov_b32_e32 v25, v0
	v_mov_b32_e32 v26, v0
	v_mov_b32_e32 v27, v0
	v_mov_b32_e32 v28, v0
	v_mov_b32_e32 v29, v0
	v_mov_b32_e32 v30, v0
	v_mov_b32_e32 v31, v0
	s_waitcnt vmcnt(0)
	s_branch .LBB0_354

; template <bool SB>
; DEV void attn_pass(const bf16_t* __restrict__ proj, int qcol, int kcol, int vcol, int q0, f32x16 (&o)[4], float& l_out, unsigned char* lds) {
;     ...
;     if (j <= jw) {
;       const unsigned char* Ks = K_lds + buf * 16384;
;       f32x16 p0 = {}, p1 = {};
; #pragma unroll
;       for (int d0 = 0; d0 < NDK; ++d0) { const int cb = ((d0 * 16 + hi * 8) * 2) ^ ((r32 & 7) << 4);
;         bf16x8 b0 = *reinterpret_cast<const bf16x8*>(Ks + r32 * KROWB + cb);
;         bf16x8 b1 = *reinterpret_cast<const bf16x8*>(Ks + (32 + r32) * KROWB + cb);
;         p0 = __builtin_amdgcn_mfma_f32_32x32x16_bf16(b0, qr[d0], p0, 0, 0, 0);
;         p1 = __builtin_amdgcn_mfma_f32_32x32x16_bf16(b1, qr[d0], p1, 0, 0, 0); }
;       bf16x8 pa0, pa1, pa2, pa3;
;       if constexpr (SB) {
;         const bool diag = (j == jw); const int rl = 32 * (wid & 1) + r32;
;         float T[8], Pg[8];
;     ...
;         if (diag) {
;           SBGRP(p0, 0, 0); SBGRP(p0, 1, 0); SBGRP(p0, 2, 0); SBGRP(p0, 3, 0);
;           SBGRP(p1, 0, 32); SBGRP(p1, 1, 32); SBGRP(p1, 2, 32); SBGRP(p1, 3, 32);
;         } else {
;           SBGRPF(p0, 0, 0); SBGRPF(p0, 1, 0); SBGRPF(p0, 2, 0); SBGRPF(p0, 3, 0);
;           SBGRPF(p1, 0, 32); SBGRPF(p1, 1, 32); SBGRPF(p1, 2, 32); SBGRPF(p1, 3, 32);
;         }
.LBB0_356:
	s_and_b32 s83, s79, 1
	v_cmp_le_i32_e32 vcc, s84, v208
	v_mov_b32_e32 v64, 0
	s_and_saveexec_b64 s[94:95], vcc
	s_cbranch_execz .LBB0_363
	s_lshl_b32 s90, s83, 14
	v_add_u32_e32 v156, s90, v223
	v_add_u32_e32 v68, v156, v224
	ds_read_b128 v[64:67], v68 offset:32768
	ds_read_b128 v[68:71], v68 offset:40960
	v_add_u32_e32 v152, v156, v225
	ds_read_b128 v[148:151], v152 offset:32768
	ds_read_b128 v[152:155], v152 offset:40960
	v_cmp_ne_u32_e32 vcc, s79, v233
	s_waitcnt lgkmcnt(3)
	v_mfma_f32_32x32x16_bf16 v[80:95], v[64:67], v[112:115], 0
	s_waitcnt lgkmcnt(2)
	v_mfma_f32_32x32x16_bf16 v[64:79], v[68:71], v[112:115], 0
	s_waitcnt lgkmcnt(1)
	v_mfma_f32_32x32x16_bf16 v[80:95], v[148:151], v[116:119], v[80:95]
	s_waitcnt lgkmcnt(0)
	v_mfma_f32_32x32x16_bf16 v[64:79], v[152:155], v[116:119], v[64:79]
	v_add_u32_e32 v152, v156, v226
	ds_read_b128 v[148:151], v152 offset:32768
	ds_read_b128 v[152:155], v152 offset:40960
	s_waitcnt lgkmcnt(1)
	v_mfma_f32_32x32x16_bf16 v[80:95], v[148:151], v[120:123], v[80:95]
	s_waitcnt lgkmcnt(0)
	v_mfma_f32_32x32x16_bf16 v[64:79], v[152:155], v[120:123], v[64:79]
	v_add_u32_e32 v152, v156, v227
	ds_read_b128 v[148:151], v152 offset:32768
	ds_read_b128 v[152:155], v152 offset:40960
	s_waitcnt lgkmcnt(1)
	v_mfma_f32_32x32x16_bf16 v[80:95], v[148:151], v[124:127], v[80:95]
	s_waitcnt lgkmcnt(0)
	v_mfma_f32_32x32x16_bf16 v[64:79], v[152:155], v[124:127], v[64:79]
	v_add_u32_e32 v152, v156, v228
	ds_read_b128 v[148:151], v152 offset:32768
	ds_read_b128 v[152:155], v152 offset:40960
	s_waitcnt lgkmcnt(1)
	v_mfma_f32_32x32x16_bf16 v[80:95], v[148:151], v[128:131], v[80:95]
	s_waitcnt lgkmcnt(0)
	v_mfma_f32_32x32x16_bf16 v[64:79], v[152:155], v[128:131], v[64:79]
	v_add_u32_e32 v152, v156, v229
	ds_read_b128 v[148:151], v152 offset:32768
	ds_read_b128 v[152:155], v152 offset:40960
	s_waitcnt lgkmcnt(1)
	v_mfma_f32_32x32x16_bf16 v[80:95], v[148:151], v[132:135], v[80:95]
	s_waitcnt lgkmcnt(0)
	v_mfma_f32_32x32x16_bf16 v[64:79], v[152:155], v[132:135], v[64:79]
	v_add_u32_e32 v152, v156, v230
	ds_read_b128 v[148:151], v152 offset:32768
	ds_read_b128 v[152:155], v152 offset:40960
	s_waitcnt lgkmcnt(1)
	v_mfma_f32_32x32x16_bf16 v[80:95], v[148:151], v[136:139], v[80:95]
	s_waitcnt lgkmcnt(0)
	v_mfma_f32_32x32x16_bf16 v[64:79], v[152:155], v[136:139], v[64:79]
	v_add_u32_e32 v152, v156, v231
	ds_read_b128 v[148:151], v152 offset:32768
	ds_read_b128 v[152:155], v152 offset:40960
	s_waitcnt lgkmcnt(1)
	v_mfma_f32_32x32x16_bf16 v[80:95], v[148:151], v[140:143], v[80:95]
	s_waitcnt lgkmcnt(0)
	v_mfma_f32_32x32x16_bf16 v[64:79], v[152:155], v[140:143], v[64:79]
	s_nop 9
	v_max_f32_e32 v80, v80, v80
	v_min_f32_e32 v80, 0x42a00000, v80
	v_exp_f32_e32 v80, v80
	s_nop 0
	v_add_f32_e32 v148, 1.0, v80
	v_rcp_f32_e32 v244, v148
	s_nop 0
	v_mul_f32_e32 v186, v80, v244
	s_and_saveexec_b64 s[96:97], vcc
	s_xor_b64 vcc, exec, s[96:97]
	s_cbranch_execz .LBB0_359
	v_max_f32_e32 v80, v81, v81
	v_min_f32_e32 v80, 0x42a00000, v80
	v_exp_f32_e32 v81, v80
	v_max_f32_e32 v80, v82, v82
	v_min_f32_e32 v80, 0x42a00000, v80
	v_max_f32_e32 v82, v83, v83
	v_exp_f32_e32 v80, v80
	v_min_f32_e32 v82, 0x42a00000, v82
	v_exp_f32_e32 v83, v82
	v_add_f32_e32 v82, 1.0, v81
	v_add_f32_e32 v148, 1.0, v80
	v_rcp_f32_e32 v149, v148
	v_add_f32_e32 v148, 1.0, v83
	v_rcp_f32_e32 v148, v148
	v_rcp_f32_e32 v150, v82
	v_mul_f32_e32 v82, v80, v149
	v_max_f32_e32 v66, v66, v66
	v_mul_f32_e32 v80, v148, v149
	v_pk_mul_f32 v[150:151], v[150:151], v[80:81] op_sel_hi:[0,1]
	v_mov_b32_e32 v187, v80
	v_max_f32_e32 v80, v84, v84
	v_min_f32_e32 v80, 0x42a00000, v80
	v_exp_f32_e32 v80, v80
	v_pk_mul_f32 v[148:149], v[148:149], v[82:83] op_sel_hi:[0,1]
	v_max_f32_e32 v83, v86, v86
	v_min_f32_e32 v83, 0x42a00000, v83
	v_add_f32_e32 v81, 1.0, v80
	v_rcp_f32_e32 v84, v81
	v_max_f32_e32 v81, v85, v85
	v_max_f32_e32 v85, v87, v87
	v_exp_f32_e32 v83, v83
	v_min_f32_e32 v85, 0x42a00000, v85
	v_exp_f32_e32 v87, v85
	v_min_f32_e32 v81, 0x42a00000, v81
	v_exp_f32_e32 v153, v81
	v_add_f32_e32 v81, 1.0, v83
	v_rcp_f32_e32 v85, v81
	v_add_f32_e32 v81, 1.0, v87
	v_rcp_f32_e32 v81, v81
	v_add_f32_e32 v86, 1.0, v153
	v_rcp_f32_e32 v154, v86
	v_mul_f32_e32 v86, v83, v85
	v_pk_mul_f32 v[158:159], v[80:81], v[84:85]
	v_mov_b32_e32 v80, v81
	v_mov_b32_e32 v152, v159
	v_pk_mul_f32 v[152:153], v[154:155], v[152:153] op_sel_hi:[0,1]
	v_mul_f32_e32 v156, v244, v150
	v_mul_f32_e32 v157, v84, v152
	v_pk_mul_f32 v[154:155], v[152:153], v[158:159]
	v_pk_mul_f32 v[152:153], v[80:81], v[86:87] op_sel_hi:[0,1]
	v_max_f32_e32 v80, v88, v88
	v_mov_b32_e32 v82, v156
	v_mov_b32_e32 v83, v157
	v_min_f32_e32 v80, 0x42a00000, v80
	v_permlane32_swap_b32_e32 v156, v82
	v_permlane32_swap_b32_e32 v157, v83
	v_exp_f32_e32 v80, v80
	v_pk_mul_f32 v[156:157], v[156:157], v[82:83]
	v_cndmask_b32_e64 v235, 1.0, v83, s[4:5]
	v_max_f32_e32 v83, v90, v90
	v_min_f32_e32 v83, 0x42a00000, v83
	v_exp_f32_e32 v84, v83
	v_max_f32_e32 v83, v91, v91
	v_add_f32_e32 v81, 1.0, v80
	v_min_f32_e32 v83, 0x42a00000, v83
	v_pk_mul_f32 v[150:151], v[186:187], v[150:151]
	v_cndmask_b32_e64 v187, 1.0, v82, s[4:5]
	v_rcp_f32_e32 v82, v81
	v_max_f32_e32 v81, v89, v89
	v_exp_f32_e32 v85, v83
	v_min_f32_e32 v81, 0x42a00000, v81
	v_exp_f32_e32 v87, v81
	v_add_f32_e32 v81, 1.0, v84
	v_rcp_f32_e32 v83, v81
	v_add_f32_e32 v81, 1.0, v85
	v_rcp_f32_e32 v81, v81
	v_add_f32_e32 v86, 1.0, v87
	v_rcp_f32_e32 v88, v86
; template <bool SB>
; DEV void attn_pass(const bf16_t* __restrict__ proj, int qcol, int kcol, int vcol, int q0, f32x16 (&o)[4], float& l_out, unsigned char* lds) {
;     ...
;         if (diag) {
;           SBGRP(p0, 0, 0); SBGRP(p0, 1, 0); SBGRP(p0, 2, 0); SBGRP(p0, 3, 0);
;           SBGRP(p1, 0, 32); SBGRP(p1, 1, 32); SBGRP(p1, 2, 32); SBGRP(p1, 3, 32);
;         } else {
;           SBGRPF(p0, 0, 0); SBGRPF(p0, 1, 0); SBGRPF(p0, 2, 0); SBGRPF(p0, 3, 0);
;           SBGRPF(p1, 0, 32); SBGRPF(p1, 1, 32); SBGRPF(p1, 2, 32); SBGRPF(p1, 3, 32);
;         }
	v_mul_f32_e32 v84, v84, v83
	v_pk_mul_f32 v[90:91], v[80:81], v[82:83]
	v_max_f32_e32 v64, v64, v64
	v_mov_b32_e32 v86, v91
	v_pk_mul_f32 v[86:87], v[88:89], v[86:87] op_sel_hi:[0,1]
	v_mul_f32_e32 v80, v82, v86
	v_mov_b32_e32 v82, v81
	v_max_f32_e32 v81, v92, v92
	v_min_f32_e32 v81, 0x42a00000, v81
	v_pk_mul_f32 v[158:159], v[82:83], v[84:85] op_sel_hi:[0,1]
	v_exp_f32_e32 v82, v81
	v_max_f32_e32 v83, v94, v94
	v_min_f32_e32 v83, 0x42a00000, v83
	v_exp_f32_e32 v85, v83
	v_max_f32_e32 v83, v95, v95
	v_add_f32_e32 v81, 1.0, v82
	v_min_f32_e32 v83, 0x42a00000, v83
	v_pk_mul_f32 v[160:161], v[86:87], v[90:91]
	v_rcp_f32_e32 v86, v81
	v_max_f32_e32 v81, v93, v93
	v_exp_f32_e32 v89, v83
	v_min_f32_e32 v81, 0x42a00000, v81
	v_exp_f32_e32 v91, v81
	v_add_f32_e32 v81, 1.0, v85
	v_rcp_f32_e32 v87, v81
	v_add_f32_e32 v81, 1.0, v89
	v_rcp_f32_e32 v83, v81
	v_add_f32_e32 v81, 1.0, v91
	v_rcp_f32_e32 v92, v81
	v_min_f32_e32 v66, 0x42a00000, v66
	v_pk_mul_f32 v[94:95], v[82:83], v[86:87]
	v_max_f32_e32 v67, v67, v67
	v_mov_b32_e32 v90, v95
	v_min_f32_e32 v64, 0x42a00000, v64
	v_exp_f32_e32 v66, v66
	v_min_f32_e32 v67, 0x42a00000, v67
	v_pk_mul_f32 v[90:91], v[92:93], v[90:91] op_sel_hi:[0,1]
	v_exp_f32_e32 v64, v64
	v_max_f32_e32 v65, v65, v65
	v_exp_f32_e32 v67, v67
	v_mul_f32_e32 v88, v85, v87
	v_mul_f32_e32 v81, v86, v90
	v_mov_b32_e32 v82, v83
	v_min_f32_e32 v65, 0x42a00000, v65
	v_mov_b32_e32 v84, v80
	v_pk_mul_f32 v[164:165], v[82:83], v[88:89] op_sel_hi:[0,1]
	v_mov_b32_e32 v85, v81
	v_exp_f32_e32 v83, v65
	v_permlane32_swap_b32_e32 v80, v84
	v_permlane32_swap_b32_e32 v81, v85
	v_add_f32_e32 v65, 1.0, v66
	v_pk_mul_f32 v[166:167], v[80:81], v[84:85]
	v_add_f32_e32 v80, 1.0, v64
	v_rcp_f32_e32 v81, v65
	v_add_f32_e32 v65, 1.0, v67
	v_rcp_f32_e32 v80, v80
	v_rcp_f32_e32 v65, v65
	v_add_f32_e32 v82, 1.0, v83
	v_cndmask_b32_e64 v236, 1.0, v84, s[4:5]
	v_rcp_f32_e32 v84, v82
	v_pk_mul_f32 v[86:87], v[64:65], v[80:81]
	v_mul_f32_e32 v66, v66, v81
	v_mov_b32_e32 v82, v87
	v_pk_mul_f32 v[82:83], v[84:85], v[82:83] op_sel_hi:[0,1]
	v_mul_f32_e32 v64, v80, v82
	v_mov_b32_e32 v80, v65
	v_max_f32_e32 v65, v68, v68
	v_min_f32_e32 v65, 0x42a00000, v65
	v_pk_mul_f32 v[168:169], v[80:81], v[66:67] op_sel_hi:[0,1]
	v_exp_f32_e32 v66, v65
	v_max_f32_e32 v67, v70, v70
	v_min_f32_e32 v67, 0x42a00000, v67
	v_pk_mul_f32 v[170:171], v[82:83], v[86:87]
	v_add_f32_e32 v65, 1.0, v66
	v_rcp_f32_e32 v80, v65
	v_max_f32_e32 v65, v69, v69
	v_exp_f32_e32 v69, v67
	v_max_f32_e32 v67, v71, v71
	v_min_f32_e32 v67, 0x42a00000, v67
	v_exp_f32_e32 v71, v67
	v_min_f32_e32 v65, 0x42a00000, v65
	v_exp_f32_e32 v83, v65
	v_add_f32_e32 v65, 1.0, v69
	v_rcp_f32_e32 v81, v65
	v_add_f32_e32 v65, 1.0, v71
	v_rcp_f32_e32 v67, v65
	v_add_f32_e32 v65, 1.0, v83
	v_rcp_f32_e32 v84, v65
	v_mul_f32_e32 v70, v69, v81
	v_pk_mul_f32 v[86:87], v[66:67], v[80:81]
	v_mov_b32_e32 v66, v67
	v_mov_b32_e32 v82, v87
	v_pk_mul_f32 v[82:83], v[84:85], v[82:83] op_sel_hi:[0,1]
	v_mul_f32_e32 v65, v80, v82
	v_mov_b32_e32 v68, v64
	v_pk_mul_f32 v[172:173], v[66:67], v[70:71] op_sel_hi:[0,1]
	v_mov_b32_e32 v69, v65
	v_max_f32_e32 v67, v74, v74
	v_permlane32_swap_b32_e32 v64, v68
	v_permlane32_swap_b32_e32 v65, v69
	v_min_f32_e32 v67, 0x42a00000, v67
	v_max_f32_e32 v66, v72, v72
	v_cndmask_b32_e64 v238, 1.0, v68, s[4:5]
	v_pk_mul_f32 v[176:177], v[64:65], v[68:69]
	v_exp_f32_e32 v68, v67
	v_max_f32_e32 v67, v75, v75
	v_min_f32_e32 v66, 0x42a00000, v66
	v_min_f32_e32 v67, 0x42a00000, v67
	v_exp_f32_e32 v66, v66
	v_cndmask_b32_e64 v239, 1.0, v69, s[4:5]
	v_max_f32_e32 v65, v73, v73
	v_exp_f32_e32 v69, v67
	v_min_f32_e32 v65, 0x42a00000, v65
	v_exp_f32_e32 v71, v65
	v_add_f32_e32 v64, 1.0, v66
	v_add_f32_e32 v65, 1.0, v68
	v_add_f32_e32 v67, 1.0, v69
	v_rcp_f32_e32 v64, v64
	v_rcp_f32_e32 v65, v65
	v_rcp_f32_e32 v67, v67
	v_add_f32_e32 v70, 1.0, v71
	v_rcp_f32_e32 v72, v70
	v_mul_f32_e32 v68, v68, v65
	v_pk_mul_f32 v[74:75], v[66:67], v[64:65]
	v_pk_mul_f32 v[162:163], v[90:91], v[94:95]
	v_mov_b32_e32 v70, v75
	v_pk_mul_f32 v[70:71], v[72:73], v[70:71] op_sel_hi:[0,1]
	v_mul_f32_e32 v65, v64, v70
	v_mov_b32_e32 v64, v67
	v_pk_mul_f32 v[178:179], v[64:65], v[68:69] op_sel_hi:[0,1]
	v_max_f32_e32 v64, v76, v76
	v_min_f32_e32 v64, 0x42a00000, v64
	v_exp_f32_e32 v64, v64
	v_max_f32_e32 v67, v78, v78
	v_mov_b32_e32 v66, v65
	v_min_f32_e32 v67, 0x42a00000, v67
	s_nop 0
	v_permlane32_swap_b32_e32 v65, v66
	v_exp_f32_e32 v68, v67
	v_max_f32_e32 v67, v79, v79
	v_mul_f32_e32 v240, v65, v66
	v_add_f32_e32 v65, 1.0, v64
	v_min_f32_e32 v67, 0x42a00000, v67
	v_cndmask_b32_e64 v241, 1.0, v66, s[4:5]
	v_rcp_f32_e32 v66, v65
	v_max_f32_e32 v65, v77, v77
	v_exp_f32_e32 v69, v67
	v_min_f32_e32 v65, 0x42a00000, v65
	v_pk_mul_f32 v[180:181], v[70:71], v[74:75]
	v_exp_f32_e32 v71, v65
	v_add_f32_e32 v65, 1.0, v68
	v_rcp_f32_e32 v67, v65
	v_add_f32_e32 v65, 1.0, v69
	v_rcp_f32_e32 v65, v65
	v_add_f32_e32 v70, 1.0, v71
	v_rcp_f32_e32 v72, v70
	v_mul_f32_e32 v68, v68, v67
	v_pk_mul_f32 v[74:75], v[64:65], v[66:67]
	v_mov_b32_e32 v64, v65
	v_mov_b32_e32 v70, v75
	v_pk_mul_f32 v[70:71], v[72:73], v[70:71] op_sel_hi:[0,1]
	v_mul_f32_e32 v242, v66, v70
	v_mov_b32_e32 v243, v242
	v_cndmask_b32_e64 v237, 1.0, v85, s[4:5]
	v_pk_mul_f32 v[174:175], v[82:83], v[86:87]
	v_pk_mul_f32 v[184:185], v[70:71], v[74:75]
	v_pk_mul_f32 v[182:183], v[64:65], v[68:69] op_sel_hi:[0,1]
	v_permlane32_swap_b32_e32 v242, v243
